# speedup vs baseline: 1.0029x; 1.0029x over previous
;   __device__ __forceinline__ u16* proj() const { return (u16*)(ws + 185 * MB); }
; template <int EPI> ...
;     ...
;       unsigned long long sqc[8];
; #pragma unroll
;       for (int m = 0; m < 8; ++m) sqc[m] = ssq_in[pm * 256 + wr * 128 + fr + m * 16];
; #pragma unroll
;       for (int m = 0; m < 8; ++m) rs[m] = rsqrtf((float)sqc[m] * SSQ_UNFIX + 1e-6f);
;     ...
;         const int ld = (EPI == EPI_PROJ) ? INW : DFF;
;         u16* gout = p.proj() + (long)(brow + wr * 128 + (lane >> 3)) * ld + bcol + wc * 64 + (lane & 7) * 8;
;         const int wswz = fr & 7, rswz = (lane >> 3) & 7;
; #pragma unroll
;         for (int h = 0; h < 2; ++h) {
; #pragma unroll
;           for (int mm = 0; mm < 4; ++mm)
; #pragma unroll
;             for (int n = 0; n < 4; ++n) {
;               f32x4 v = acc[h * 4 + mm][n] * rs[h * 4 + mm];
;               if constexpr (EPI == EPI_PROJ) {
;                 if (gate) {
; #pragma unroll
;                   for (int j = 0; j < 4; ++j) v[j] = __builtin_amdgcn_rcpf(1.0f + __expf(-v[j]));
.LBB0_145:
	s_waitcnt vmcnt(0)
	v_ffbh_u32_e32 v152, v151
	v_min_u32_e32 v152, 32, v152
	v_lshlrev_b64 v[150:151], v152, v[150:151]
	v_min_u32_e32 v150, 1, v150
	v_or_b32_e32 v150, v151, v150
	v_ffbh_u32_e32 v151, v149
	v_min_u32_e32 v151, 32, v151
	v_lshlrev_b64 v[148:149], v151, v[148:149]
	v_min_u32_e32 v148, 1, v148
	v_or_b32_e32 v148, v149, v148
	v_cvt_f32_u32_e32 v148, v148
	v_cvt_f32_u32_e32 v150, v150
	v_sub_u32_e32 v151, 32, v151
	v_sub_u32_e32 v152, 32, v152
	v_ldexp_f32 v148, v148, v151
	v_fmamk_f32 v148, v148, 0x30800000, v160
	v_ldexp_f32 v150, v150, v152
	v_mul_f32_e32 v151, 0x4b800000, v148
	v_cmp_gt_f32_e64 s[4:5], s61, v148
	v_fmamk_f32 v150, v150, 0x30800000, v160
	v_mul_f32_e32 v152, 0x4b800000, v150
	v_cndmask_b32_e64 v148, v148, v151, s[4:5]
	v_ffbh_u32_e32 v151, v147
	v_cmp_gt_f32_e32 vcc, s61, v150
	v_min_u32_e32 v151, 32, v151
	v_lshlrev_b64 v[146:147], v151, v[146:147]
	v_cndmask_b32_e32 v150, v150, v152, vcc
	v_rsq_f32_e32 v150, v150
	v_min_u32_e32 v146, 1, v146
	v_or_b32_e32 v146, v147, v146
	v_cvt_f32_u32_e32 v146, v146
	v_mul_f32_e32 v149, 0x45800000, v150
	v_cndmask_b32_e32 v150, v150, v149, vcc
	v_sub_u32_e32 v149, 32, v151
	v_ldexp_f32 v146, v146, v149
	v_fmamk_f32 v146, v146, 0x30800000, v160
	v_mul_f32_e32 v149, 0x4b800000, v146
	v_cmp_gt_f32_e32 vcc, s61, v146
	v_rsq_f32_e32 v148, v148
	s_nop 0
	v_cndmask_b32_e32 v146, v146, v149, vcc
	v_ffbh_u32_e32 v149, v145
	v_min_u32_e32 v149, 32, v149
	v_lshlrev_b64 v[144:145], v149, v[144:145]
	v_min_u32_e32 v144, 1, v144
	v_or_b32_e32 v144, v145, v144
	v_cvt_f32_u32_e32 v144, v144
	v_mul_f32_e32 v147, 0x45800000, v148
	v_cndmask_b32_e64 v148, v148, v147, s[4:5]
	v_sub_u32_e32 v147, 32, v149
	v_ldexp_f32 v144, v144, v147
	v_fmamk_f32 v144, v144, 0x30800000, v160
	v_mul_f32_e32 v147, 0x4b800000, v144
	v_cmp_gt_f32_e64 s[4:5], s61, v144
	v_rsq_f32_e32 v146, v146
	v_mov_b32_e32 v149, v3
	v_cndmask_b32_e64 v144, v144, v147, s[4:5]
	v_ffbh_u32_e32 v147, v143
	v_min_u32_e32 v147, 32, v147
	v_lshlrev_b64 v[142:143], v147, v[142:143]
	v_min_u32_e32 v142, 1, v142
	v_or_b32_e32 v142, v143, v142
	v_cvt_f32_u32_e32 v142, v142
	v_mul_f32_e32 v145, 0x45800000, v146
	v_cndmask_b32_e32 v146, v146, v145, vcc
	v_sub_u32_e32 v145, 32, v147
	v_ldexp_f32 v142, v142, v145
	v_fmamk_f32 v142, v142, 0x30800000, v160
	v_mul_f32_e32 v145, 0x4b800000, v142
	v_cmp_gt_f32_e32 vcc, s61, v142
	v_rsq_f32_e32 v144, v144
	s_nop 0
	v_cndmask_b32_e32 v142, v142, v145, vcc
	v_ffbh_u32_e32 v145, v141
	v_min_u32_e32 v145, 32, v145
	v_lshlrev_b64 v[140:141], v145, v[140:141]
	v_min_u32_e32 v140, 1, v140
	v_or_b32_e32 v140, v141, v140
	v_cvt_f32_u32_e32 v140, v140
	v_mul_f32_e32 v143, 0x45800000, v144
	v_cndmask_b32_e64 v144, v144, v143, s[4:5]
	v_sub_u32_e32 v143, 32, v145
	v_ldexp_f32 v140, v140, v143
	v_fmamk_f32 v140, v140, 0x30800000, v160
	v_rsq_f32_e32 v142, v142
	v_mul_f32_e32 v143, 0x4b800000, v140
	v_cmp_gt_f32_e64 s[4:5], s61, v140
	v_and_b32_e32 v147, 15, v149
	v_mul_f32_e32 v141, 0x45800000, v142
	v_cndmask_b32_e64 v140, v140, v143, s[4:5]
	v_ffbh_u32_e32 v143, v139
	v_min_u32_e32 v143, 32, v143
	v_lshlrev_b64 v[138:139], v143, v[138:139]
	v_min_u32_e32 v138, 1, v138
	v_or_b32_e32 v138, v139, v138
	v_cndmask_b32_e32 v142, v142, v141, vcc
	v_sub_u32_e32 v141, 32, v143
	v_ffbh_u32_e32 v143, v137
	v_cvt_f32_u32_e32 v138, v138
	v_min_u32_e32 v143, 32, v143
	v_lshlrev_b64 v[136:137], v143, v[136:137]
	v_min_u32_e32 v136, 1, v136
	v_or_b32_e32 v136, v137, v136
	v_ldexp_f32 v138, v138, v141
	v_cvt_f32_u32_e32 v136, v136
	v_fmamk_f32 v138, v138, 0x30800000, v160
	v_mul_f32_e32 v141, 0x4b800000, v138
	v_cmp_gt_f32_e32 vcc, s61, v138
	v_rsq_f32_e32 v140, v140
	v_bfe_u32 v145, v149, 4, 2
	v_cndmask_b32_e32 v137, v138, v141, vcc
	v_sub_u32_e32 v138, 32, v143
	v_ldexp_f32 v136, v136, v138
	v_fmamk_f32 v136, v136, 0x30800000, v160
	v_mul_f32_e32 v138, 0x4b800000, v136
	v_cmp_gt_f32_e64 s[6:7], s61, v136
	v_rsq_f32_e32 v137, v137
	v_mul_f32_e32 v139, 0x45800000, v140
	v_cndmask_b32_e64 v136, v136, v138, s[6:7]
	v_rsq_f32_e32 v136, v136
	v_mul_f32_e32 v138, 0x45800000, v137
	v_cndmask_b32_e32 v138, v137, v138, vcc
	v_cndmask_b32_e64 v140, v140, v139, s[4:5]
	v_mul_f32_e32 v137, 0x45800000, v136
	v_cndmask_b32_e64 v136, v136, v137, s[6:7]
	s_lshl_b32 s6, s51, 8
	v_ashrrev_i32_e32 v139, 1, v149
	s_and_b32 s4, s51, -2
	v_ashrrev_i32_e32 v137, 6, v149
	v_and_b32_e32 v139, 0xffffff80, v139
	s_cmp_lg_u32 s4, 4
	v_and_b32_e32 v143, 3, v137
	v_add_u32_e32 v139, s16, v139
	s_cselect_b64 s[16:17], -1, 0
	s_cmp_lg_u32 s51, 8
	s_cselect_b64 s[4:5], -1, 0
	v_cmp_gt_u32_e32 vcc, 2, v143
	s_or_b64 s[4:5], s[4:5], vcc
	v_lshl_add_u32 v137, v137, 13, v169
	v_lshlrev_b32_e32 v141, 6, v143
	s_and_b64 s[4:5], s[16:17], s[4:5]
	s_and_saveexec_b64 s[22:23], s[4:5]
	s_xor_b64 s[22:23], exec, s[22:23]
	s_cbranch_execz .LBB0_275
	v_and_b32_e32 v186, 63, v3
	v_lshrrev_b32_e32 v187, 6, v3
	v_and_b32_e32 v188, 15, v3
	v_bfe_u32 v189, v3, 4, 2
	v_lshlrev_b32_e32 v190, 13, v187
	v_add_u32_e32 v190, 0x10000, v190
	v_lshl_add_u32 v191, v188, 7, v190
	v_and_b32_e32 v192, 1, v189
	v_lshl_add_u32 v191, v192, 3, v191
	v_lshrrev_b32_e32 v194, 1, v189
	v_and_b32_e32 v195, 7, v188
	v_or_b32_e32 v192, 0, v194
	v_xor_b32_e32 v192, v192, v195
	v_lshl_add_u32 v196, v192, 4, v191
	v_or_b32_e32 v192, 2, v194
	v_xor_b32_e32 v192, v192, v195
	v_lshl_add_u32 v197, v192, 4, v191
	v_or_b32_e32 v192, 4, v194
	v_xor_b32_e32 v192, v192, v195
	v_lshl_add_u32 v198, v192, 4, v191
	v_or_b32_e32 v192, 6, v194
	v_xor_b32_e32 v192, v192, v195
	v_lshl_add_u32 v199, v192, 4, v191
	v_lshrrev_b32_e32 v200, 3, v186
	v_and_b32_e32 v201, 7, v186
	v_xor_b32_e32 v192, v201, v200
	v_lshl_add_u32 v202, v200, 7, v190
	v_lshl_add_u32 v202, v192, 4, v202
	v_lshrrev_b32_e32 v192, 2, v187
	v_lshl_add_u32 v203, v192, 7, v200
	s_lshl_b32 s7, s24, 8
	v_add_u32_e32 v203, s7, v203
	v_mov_b64_e32 v[204:205], s[38:39]
	v_mad_u64_u32 v[204:205], s[4:5], v203, s88, v[204:205]
	v_and_b32_e32 v192, 3, v187
	v_lshlrev_b32_e32 v192, 7, v192
	v_lshl_add_u32 v192, v201, 4, v192
	s_lshl_b32 s7, s51, 9
	v_add_u32_e32 v192, s7, v192
	v_mov_b32_e32 v193, v2
	v_lshl_add_u64 v[204:205], v[204:205], 0, v[192:193]
	s_mov_b32 s5, 0
	s_cmp_gt_i32 s51, 8
	v_pk_mul_f32 v[132:133], v[132:133], v[150:151] op_sel_hi:[1,0]
	v_pk_mul_f32 v[134:135], v[134:135], v[150:151] op_sel_hi:[1,0]
	v_pk_mul_f32 v[128:129], v[128:129], v[150:151] op_sel_hi:[1,0]
	v_pk_mul_f32 v[130:131], v[130:131], v[150:151] op_sel_hi:[1,0]
	s_cbranch_scc0 .Lp1e_1
	v_mul_f32_e32 v132, 0xbfb8aa3b, v132
	v_mul_f32_e32 v133, 0xbfb8aa3b, v133
	v_mul_f32_e32 v134, 0xbfb8aa3b, v134
	v_mul_f32_e32 v135, 0xbfb8aa3b, v135
	v_exp_f32_e32 v132, v132
	v_exp_f32_e32 v133, v133
	v_exp_f32_e32 v134, v134
	v_exp_f32_e32 v135, v135
	v_add_f32_e32 v132, 1.0, v132
	v_add_f32_e32 v133, 1.0, v133
	v_add_f32_e32 v134, 1.0, v134
	v_add_f32_e32 v135, 1.0, v135
	v_rcp_f32_e32 v132, v132
	v_rcp_f32_e32 v133, v133
	v_rcp_f32_e32 v134, v134
	v_rcp_f32_e32 v135, v135
; template <int EPI> ...
;     ...
;         for (int h = 0; h < 2; ++h) {
; #pragma unroll
;           for (int mm = 0; mm < 4; ++mm)
; #pragma unroll
;             for (int n = 0; n < 4; ++n) {
;               f32x4 v = acc[h * 4 + mm][n] * rs[h * 4 + mm];
;               if constexpr (EPI == EPI_PROJ) {
;                 if (gate) {
; #pragma unroll
;                   for (int j = 0; j < 4; ++j) v[j] = __builtin_amdgcn_rcpf(1.0f + __expf(-v[j]));
;                 }
;               } else {
; #pragma unroll
;                 for (int j = 0; j < 4; ++j) { float r = fmaxf(v[j], 0.f); v[j] = r * r; }
;               }
;               u32x2 o = {pack2(v[0], v[1]), pack2(v[2], v[3])};
;               *(u32x2*)(wst + (mm * 16 + fr) * 128 + (((n * 2 + (fq >> 1)) ^ wswz) << 4) + (fq & 1) * 8) = o;
.Lp1e_1:
	v_cvt_pk_bf16_f32 v206, v132, v133
	v_cvt_pk_bf16_f32 v207, v134, v135
	ds_write_b64 v196, v[206:207]
	v_pk_mul_f32 v[120:121], v[120:121], v[150:151] op_sel_hi:[1,0]
	v_pk_mul_f32 v[122:123], v[122:123], v[150:151] op_sel_hi:[1,0]
	s_cbranch_scc0 .Lp1e_2
	v_mul_f32_e32 v128, 0xbfb8aa3b, v128
	v_mul_f32_e32 v129, 0xbfb8aa3b, v129
	v_mul_f32_e32 v130, 0xbfb8aa3b, v130
	v_mul_f32_e32 v131, 0xbfb8aa3b, v131
	v_exp_f32_e32 v128, v128
	v_exp_f32_e32 v129, v129
	v_exp_f32_e32 v130, v130
	v_exp_f32_e32 v131, v131
	v_add_f32_e32 v128, 1.0, v128
	v_add_f32_e32 v129, 1.0, v129
	v_add_f32_e32 v130, 1.0, v130
	v_add_f32_e32 v131, 1.0, v131
	v_rcp_f32_e32 v128, v128
	v_rcp_f32_e32 v129, v129
	v_rcp_f32_e32 v130, v130
	v_rcp_f32_e32 v131, v131
.Lp1e_2:
	v_cvt_pk_bf16_f32 v208, v128, v129
	v_cvt_pk_bf16_f32 v209, v130, v131
	ds_write_b64 v197, v[208:209]
	v_pk_mul_f32 v[112:113], v[112:113], v[150:151] op_sel_hi:[1,0]
	v_pk_mul_f32 v[114:115], v[114:115], v[150:151] op_sel_hi:[1,0]
	s_cbranch_scc0 .Lp1e_3
	v_mul_f32_e32 v120, 0xbfb8aa3b, v120
	v_mul_f32_e32 v121, 0xbfb8aa3b, v121
	v_mul_f32_e32 v122, 0xbfb8aa3b, v122
	v_mul_f32_e32 v123, 0xbfb8aa3b, v123
	v_exp_f32_e32 v120, v120
	v_exp_f32_e32 v121, v121
	v_exp_f32_e32 v122, v122
	v_exp_f32_e32 v123, v123
	v_add_f32_e32 v120, 1.0, v120
	v_add_f32_e32 v121, 1.0, v121
	v_add_f32_e32 v122, 1.0, v122
	v_add_f32_e32 v123, 1.0, v123
	v_rcp_f32_e32 v120, v120
	v_rcp_f32_e32 v121, v121
	v_rcp_f32_e32 v122, v122
	v_rcp_f32_e32 v123, v123
.Lp1e_3:
	v_cvt_pk_bf16_f32 v210, v120, v121
	v_cvt_pk_bf16_f32 v211, v122, v123
	ds_write_b64 v198, v[210:211]
	v_pk_mul_f32 v[124:125], v[124:125], v[148:149] op_sel_hi:[1,0]
	v_pk_mul_f32 v[126:127], v[126:127], v[148:149] op_sel_hi:[1,0]
	s_cbranch_scc0 .Lp1e_4
	v_mul_f32_e32 v112, 0xbfb8aa3b, v112
	v_mul_f32_e32 v113, 0xbfb8aa3b, v113
	v_mul_f32_e32 v114, 0xbfb8aa3b, v114
	v_mul_f32_e32 v115, 0xbfb8aa3b, v115
	v_exp_f32_e32 v112, v112
	v_exp_f32_e32 v113, v113
	v_exp_f32_e32 v114, v114
	v_exp_f32_e32 v115, v115
	v_add_f32_e32 v112, 1.0, v112
	v_add_f32_e32 v113, 1.0, v113
	v_add_f32_e32 v114, 1.0, v114
	v_add_f32_e32 v115, 1.0, v115
	v_rcp_f32_e32 v112, v112
	v_rcp_f32_e32 v113, v113
	v_rcp_f32_e32 v114, v114
	v_rcp_f32_e32 v115, v115
.Lp1e_4:
	v_cvt_pk_bf16_f32 v212, v112, v113
	v_cvt_pk_bf16_f32 v213, v114, v115
	ds_write_b64 v199, v[212:213]
	v_pk_mul_f32 v[116:117], v[116:117], v[148:149] op_sel_hi:[1,0]
	v_pk_mul_f32 v[118:119], v[118:119], v[148:149] op_sel_hi:[1,0]
	s_cbranch_scc0 .Lp1e_5
	v_mul_f32_e32 v124, 0xbfb8aa3b, v124
	v_mul_f32_e32 v125, 0xbfb8aa3b, v125
	v_mul_f32_e32 v126, 0xbfb8aa3b, v126
	v_mul_f32_e32 v127, 0xbfb8aa3b, v127
	v_exp_f32_e32 v124, v124
	v_exp_f32_e32 v125, v125
	v_exp_f32_e32 v126, v126
	v_exp_f32_e32 v127, v127
	v_add_f32_e32 v124, 1.0, v124
	v_add_f32_e32 v125, 1.0, v125
	v_add_f32_e32 v126, 1.0, v126
	v_add_f32_e32 v127, 1.0, v127
	v_rcp_f32_e32 v124, v124
	v_rcp_f32_e32 v125, v125
	v_rcp_f32_e32 v126, v126
	v_rcp_f32_e32 v127, v127
.Lp1e_5:
	v_cvt_pk_bf16_f32 v206, v124, v125
	v_cvt_pk_bf16_f32 v207, v126, v127
	ds_write_b64 v196, v[206:207] offset:2048
	v_pk_mul_f32 v[104:105], v[104:105], v[148:149] op_sel_hi:[1,0]
	v_pk_mul_f32 v[106:107], v[106:107], v[148:149] op_sel_hi:[1,0]
	s_cbranch_scc0 .Lp1e_6
	v_mul_f32_e32 v116, 0xbfb8aa3b, v116
	v_mul_f32_e32 v117, 0xbfb8aa3b, v117
	v_mul_f32_e32 v118, 0xbfb8aa3b, v118
	v_mul_f32_e32 v119, 0xbfb8aa3b, v119
	v_exp_f32_e32 v116, v116
	v_exp_f32_e32 v117, v117
	v_exp_f32_e32 v118, v118
	v_exp_f32_e32 v119, v119
	v_add_f32_e32 v116, 1.0, v116
	v_add_f32_e32 v117, 1.0, v117
	v_add_f32_e32 v118, 1.0, v118
	v_add_f32_e32 v119, 1.0, v119
	v_rcp_f32_e32 v116, v116
	v_rcp_f32_e32 v117, v117
	v_rcp_f32_e32 v118, v118
	v_rcp_f32_e32 v119, v119
.Lp1e_6:
	v_cvt_pk_bf16_f32 v208, v116, v117
	v_cvt_pk_bf16_f32 v209, v118, v119
	ds_write_b64 v197, v[208:209] offset:2048
	v_pk_mul_f32 v[96:97], v[96:97], v[148:149] op_sel_hi:[1,0]
	v_pk_mul_f32 v[98:99], v[98:99], v[148:149] op_sel_hi:[1,0]
	s_cbranch_scc0 .Lp1e_7
	v_mul_f32_e32 v104, 0xbfb8aa3b, v104
	v_mul_f32_e32 v105, 0xbfb8aa3b, v105
	v_mul_f32_e32 v106, 0xbfb8aa3b, v106
	v_mul_f32_e32 v107, 0xbfb8aa3b, v107
	v_exp_f32_e32 v104, v104
	v_exp_f32_e32 v105, v105
	v_exp_f32_e32 v106, v106
	v_exp_f32_e32 v107, v107
	v_add_f32_e32 v104, 1.0, v104
	v_add_f32_e32 v105, 1.0, v105
	v_add_f32_e32 v106, 1.0, v106
	v_add_f32_e32 v107, 1.0, v107
	v_rcp_f32_e32 v104, v104
	v_rcp_f32_e32 v105, v105
	v_rcp_f32_e32 v106, v106
	v_rcp_f32_e32 v107, v107
.Lp1e_7:
	v_cvt_pk_bf16_f32 v210, v104, v105
	v_cvt_pk_bf16_f32 v211, v106, v107
	ds_write_b64 v198, v[210:211] offset:2048
	v_pk_mul_f32 v[108:109], v[108:109], v[146:147] op_sel_hi:[1,0]
	v_pk_mul_f32 v[110:111], v[110:111], v[146:147] op_sel_hi:[1,0]
	s_cbranch_scc0 .Lp1e_8
	v_mul_f32_e32 v96, 0xbfb8aa3b, v96
	v_mul_f32_e32 v97, 0xbfb8aa3b, v97
	v_mul_f32_e32 v98, 0xbfb8aa3b, v98
	v_mul_f32_e32 v99, 0xbfb8aa3b, v99
	v_exp_f32_e32 v96, v96
	v_exp_f32_e32 v97, v97
	v_exp_f32_e32 v98, v98
	v_exp_f32_e32 v99, v99
	v_add_f32_e32 v96, 1.0, v96
	v_add_f32_e32 v97, 1.0, v97
	v_add_f32_e32 v98, 1.0, v98
	v_add_f32_e32 v99, 1.0, v99
	v_rcp_f32_e32 v96, v96
	v_rcp_f32_e32 v97, v97
	v_rcp_f32_e32 v98, v98
	v_rcp_f32_e32 v99, v99
.Lp1e_8:
	v_cvt_pk_bf16_f32 v212, v96, v97
	v_cvt_pk_bf16_f32 v213, v98, v99
	ds_write_b64 v199, v[212:213] offset:2048
	v_pk_mul_f32 v[100:101], v[100:101], v[146:147] op_sel_hi:[1,0]
	v_pk_mul_f32 v[102:103], v[102:103], v[146:147] op_sel_hi:[1,0]
	s_cbranch_scc0 .Lp1e_9
	v_mul_f32_e32 v108, 0xbfb8aa3b, v108
	v_mul_f32_e32 v109, 0xbfb8aa3b, v109
	v_mul_f32_e32 v110, 0xbfb8aa3b, v110
	v_mul_f32_e32 v111, 0xbfb8aa3b, v111
	v_exp_f32_e32 v108, v108
	v_exp_f32_e32 v109, v109
	v_exp_f32_e32 v110, v110
	v_exp_f32_e32 v111, v111
	v_add_f32_e32 v108, 1.0, v108
	v_add_f32_e32 v109, 1.0, v109
	v_add_f32_e32 v110, 1.0, v110
	v_add_f32_e32 v111, 1.0, v111
	v_rcp_f32_e32 v108, v108
	v_rcp_f32_e32 v109, v109
	v_rcp_f32_e32 v110, v110
	v_rcp_f32_e32 v111, v111
; template <int EPI> ...
;     ...
;         for (int h = 0; h < 2; ++h) {
; #pragma unroll
;           for (int mm = 0; mm < 4; ++mm)
; #pragma unroll
;             for (int n = 0; n < 4; ++n) {
;               f32x4 v = acc[h * 4 + mm][n] * rs[h * 4 + mm];
;               if constexpr (EPI == EPI_PROJ) {
;                 if (gate) {
; #pragma unroll
;                   for (int j = 0; j < 4; ++j) v[j] = __builtin_amdgcn_rcpf(1.0f + __expf(-v[j]));
;                 }
;               } else {
; #pragma unroll
;                 for (int j = 0; j < 4; ++j) { float r = fmaxf(v[j], 0.f); v[j] = r * r; }
;               }
;               u32x2 o = {pack2(v[0], v[1]), pack2(v[2], v[3])};
;               *(u32x2*)(wst + (mm * 16 + fr) * 128 + (((n * 2 + (fq >> 1)) ^ wswz) << 4) + (fq & 1) * 8) = o;
.Lp1e_9:
	v_cvt_pk_bf16_f32 v206, v108, v109
	v_cvt_pk_bf16_f32 v207, v110, v111
	ds_write_b64 v196, v[206:207] offset:4096
	v_pk_mul_f32 v[88:89], v[88:89], v[146:147] op_sel_hi:[1,0]
	v_pk_mul_f32 v[90:91], v[90:91], v[146:147] op_sel_hi:[1,0]
	s_cbranch_scc0 .Lp1e_10
	v_mul_f32_e32 v100, 0xbfb8aa3b, v100
	v_mul_f32_e32 v101, 0xbfb8aa3b, v101
	v_mul_f32_e32 v102, 0xbfb8aa3b, v102
	v_mul_f32_e32 v103, 0xbfb8aa3b, v103
	v_exp_f32_e32 v100, v100
	v_exp_f32_e32 v101, v101
	v_exp_f32_e32 v102, v102
	v_exp_f32_e32 v103, v103
	v_add_f32_e32 v100, 1.0, v100
	v_add_f32_e32 v101, 1.0, v101
	v_add_f32_e32 v102, 1.0, v102
	v_add_f32_e32 v103, 1.0, v103
	v_rcp_f32_e32 v100, v100
	v_rcp_f32_e32 v101, v101
	v_rcp_f32_e32 v102, v102
	v_rcp_f32_e32 v103, v103
.Lp1e_10:
	v_cvt_pk_bf16_f32 v208, v100, v101
	v_cvt_pk_bf16_f32 v209, v102, v103
	ds_write_b64 v197, v[208:209] offset:4096
	v_pk_mul_f32 v[80:81], v[80:81], v[146:147] op_sel_hi:[1,0]
	v_pk_mul_f32 v[82:83], v[82:83], v[146:147] op_sel_hi:[1,0]
	s_cbranch_scc0 .Lp1e_11
	v_mul_f32_e32 v88, 0xbfb8aa3b, v88
	v_mul_f32_e32 v89, 0xbfb8aa3b, v89
	v_mul_f32_e32 v90, 0xbfb8aa3b, v90
	v_mul_f32_e32 v91, 0xbfb8aa3b, v91
	v_exp_f32_e32 v88, v88
	v_exp_f32_e32 v89, v89
	v_exp_f32_e32 v90, v90
	v_exp_f32_e32 v91, v91
	v_add_f32_e32 v88, 1.0, v88
	v_add_f32_e32 v89, 1.0, v89
	v_add_f32_e32 v90, 1.0, v90
	v_add_f32_e32 v91, 1.0, v91
	v_rcp_f32_e32 v88, v88
	v_rcp_f32_e32 v89, v89
	v_rcp_f32_e32 v90, v90
	v_rcp_f32_e32 v91, v91
.Lp1e_11:
	v_cvt_pk_bf16_f32 v210, v88, v89
	v_cvt_pk_bf16_f32 v211, v90, v91
	ds_write_b64 v198, v[210:211] offset:4096
	v_pk_mul_f32 v[92:93], v[92:93], v[144:145] op_sel_hi:[1,0]
	v_pk_mul_f32 v[94:95], v[94:95], v[144:145] op_sel_hi:[1,0]
	s_cbranch_scc0 .Lp1e_12
	v_mul_f32_e32 v80, 0xbfb8aa3b, v80
	v_mul_f32_e32 v81, 0xbfb8aa3b, v81
	v_mul_f32_e32 v82, 0xbfb8aa3b, v82
	v_mul_f32_e32 v83, 0xbfb8aa3b, v83
	v_exp_f32_e32 v80, v80
	v_exp_f32_e32 v81, v81
	v_exp_f32_e32 v82, v82
	v_exp_f32_e32 v83, v83
	v_add_f32_e32 v80, 1.0, v80
	v_add_f32_e32 v81, 1.0, v81
	v_add_f32_e32 v82, 1.0, v82
	v_add_f32_e32 v83, 1.0, v83
	v_rcp_f32_e32 v80, v80
	v_rcp_f32_e32 v81, v81
	v_rcp_f32_e32 v82, v82
	v_rcp_f32_e32 v83, v83
.Lp1e_12:
	v_cvt_pk_bf16_f32 v212, v80, v81
	v_cvt_pk_bf16_f32 v213, v82, v83
	ds_write_b64 v199, v[212:213] offset:4096
	v_pk_mul_f32 v[84:85], v[84:85], v[144:145] op_sel_hi:[1,0]
	v_pk_mul_f32 v[86:87], v[86:87], v[144:145] op_sel_hi:[1,0]
	s_cbranch_scc0 .Lp1e_13
	v_mul_f32_e32 v92, 0xbfb8aa3b, v92
	v_mul_f32_e32 v93, 0xbfb8aa3b, v93
	v_mul_f32_e32 v94, 0xbfb8aa3b, v94
	v_mul_f32_e32 v95, 0xbfb8aa3b, v95
	v_exp_f32_e32 v92, v92
	v_exp_f32_e32 v93, v93
	v_exp_f32_e32 v94, v94
	v_exp_f32_e32 v95, v95
	v_add_f32_e32 v92, 1.0, v92
	v_add_f32_e32 v93, 1.0, v93
	v_add_f32_e32 v94, 1.0, v94
	v_add_f32_e32 v95, 1.0, v95
	v_rcp_f32_e32 v92, v92
	v_rcp_f32_e32 v93, v93
	v_rcp_f32_e32 v94, v94
	v_rcp_f32_e32 v95, v95
.Lp1e_13:
	v_cvt_pk_bf16_f32 v206, v92, v93
	v_cvt_pk_bf16_f32 v207, v94, v95
	ds_write_b64 v196, v[206:207] offset:6144
	v_pk_mul_f32 v[72:73], v[72:73], v[144:145] op_sel_hi:[1,0]
	v_pk_mul_f32 v[74:75], v[74:75], v[144:145] op_sel_hi:[1,0]
	s_cbranch_scc0 .Lp1e_14
	v_mul_f32_e32 v84, 0xbfb8aa3b, v84
	v_mul_f32_e32 v85, 0xbfb8aa3b, v85
	v_mul_f32_e32 v86, 0xbfb8aa3b, v86
	v_mul_f32_e32 v87, 0xbfb8aa3b, v87
	v_exp_f32_e32 v84, v84
	v_exp_f32_e32 v85, v85
	v_exp_f32_e32 v86, v86
	v_exp_f32_e32 v87, v87
	v_add_f32_e32 v84, 1.0, v84
	v_add_f32_e32 v85, 1.0, v85
	v_add_f32_e32 v86, 1.0, v86
	v_add_f32_e32 v87, 1.0, v87
	v_rcp_f32_e32 v84, v84
	v_rcp_f32_e32 v85, v85
	v_rcp_f32_e32 v86, v86
	v_rcp_f32_e32 v87, v87
.Lp1e_14:
	v_cvt_pk_bf16_f32 v208, v84, v85
	v_cvt_pk_bf16_f32 v209, v86, v87
	ds_write_b64 v197, v[208:209] offset:6144
	v_pk_mul_f32 v[64:65], v[64:65], v[144:145] op_sel_hi:[1,0]
	v_pk_mul_f32 v[66:67], v[66:67], v[144:145] op_sel_hi:[1,0]
	s_cbranch_scc0 .Lp1e_15
	v_mul_f32_e32 v72, 0xbfb8aa3b, v72
	v_mul_f32_e32 v73, 0xbfb8aa3b, v73
	v_mul_f32_e32 v74, 0xbfb8aa3b, v74
	v_mul_f32_e32 v75, 0xbfb8aa3b, v75
	v_exp_f32_e32 v72, v72
	v_exp_f32_e32 v73, v73
	v_exp_f32_e32 v74, v74
	v_exp_f32_e32 v75, v75
	v_add_f32_e32 v72, 1.0, v72
	v_add_f32_e32 v73, 1.0, v73
	v_add_f32_e32 v74, 1.0, v74
	v_add_f32_e32 v75, 1.0, v75
	v_rcp_f32_e32 v72, v72
	v_rcp_f32_e32 v73, v73
	v_rcp_f32_e32 v74, v74
	v_rcp_f32_e32 v75, v75
.Lp1e_15:
	v_cvt_pk_bf16_f32 v210, v72, v73
	v_cvt_pk_bf16_f32 v211, v74, v75
	ds_write_b64 v198, v[210:211] offset:6144
	s_cbranch_scc0 .Lp1e_16
	v_mul_f32_e32 v64, 0xbfb8aa3b, v64
	v_mul_f32_e32 v65, 0xbfb8aa3b, v65
	v_mul_f32_e32 v66, 0xbfb8aa3b, v66
	v_mul_f32_e32 v67, 0xbfb8aa3b, v67
	v_exp_f32_e32 v64, v64
	v_exp_f32_e32 v65, v65
	v_exp_f32_e32 v66, v66
	v_exp_f32_e32 v67, v67
	v_add_f32_e32 v64, 1.0, v64
	v_add_f32_e32 v65, 1.0, v65
	v_add_f32_e32 v66, 1.0, v66
	v_add_f32_e32 v67, 1.0, v67
	v_rcp_f32_e32 v64, v64
	v_rcp_f32_e32 v65, v65
	v_rcp_f32_e32 v66, v66
	v_rcp_f32_e32 v67, v67
; #define WAIT_V(n) asm volatile("s_waitcnt vmcnt(%0)" ::"n"(n) : "memory")
; #define LDS_FENCE() asm volatile("s_waitcnt lgkmcnt(0)" ::: "memory")
; template <int EPI> ...
;     ...
;               f32x4 v = acc[h * 4 + mm][n] * rs[h * 4 + mm];
;               if constexpr (EPI == EPI_PROJ) {
;                 if (gate) {
; #pragma unroll
;                   for (int j = 0; j < 4; ++j) v[j] = __builtin_amdgcn_rcpf(1.0f + __expf(-v[j]));
;                 }
;               } else {
; #pragma unroll
;                 for (int j = 0; j < 4; ++j) { float r = fmaxf(v[j], 0.f); v[j] = r * r; }
;               }
;               u32x2 o = {pack2(v[0], v[1]), pack2(v[2], v[3])};
;               *(u32x2*)(wst + (mm * 16 + fr) * 128 + (((n * 2 + (fq >> 1)) ^ wswz) << 4) + (fq & 1) * 8) = o;
;     ...
;           LDS_FENCE();
;           if (h == 0) WAIT_V(0);
; #pragma unroll
;           for (int i = 0; i < 8; ++i) {
;             const u32x4 d = *(const u32x4*)(wst + (i * 8 + (lane >> 3)) * 128 + (((lane & 7) ^ rswz) << 4));
;             *(u32x4*)(gout + (long)(h * 64 + i * 8) * ld) = d;
.Lp1e_16:
	v_cvt_pk_bf16_f32 v212, v64, v65
	v_cvt_pk_bf16_f32 v213, v66, v67
	ds_write_b64 v199, v[212:213] offset:6144
	s_waitcnt lgkmcnt(0)
	s_waitcnt vmcnt(0)
	ds_read_b128 v[222:225], v202
	ds_read_b128 v[226:229], v202 offset:1024
	ds_read_b128 v[230:233], v202 offset:2048
	ds_read_b128 v[234:237], v202 offset:3072
	ds_read_b128 v[238:241], v202 offset:4096
	ds_read_b128 v[242:245], v202 offset:5120
	ds_read_b128 v[246:249], v202 offset:6144
	ds_read_b128 v[250:253], v202 offset:7168
	s_waitcnt lgkmcnt(7)
	global_store_dwordx4 v[204:205], v[222:225], off
	s_mov_b32 s4, 0x11000
	v_lshl_add_u64 v[216:217], v[204:205], 0, s[4:5]
	s_waitcnt lgkmcnt(6)
	global_store_dwordx4 v[216:217], v[226:229], off
	s_mov_b32 s4, 0x22000
	v_lshl_add_u64 v[218:219], v[204:205], 0, s[4:5]
	s_waitcnt lgkmcnt(5)
	global_store_dwordx4 v[218:219], v[230:233], off
	s_mov_b32 s4, 0x33000
	v_lshl_add_u64 v[220:221], v[204:205], 0, s[4:5]
	s_waitcnt lgkmcnt(4)
	global_store_dwordx4 v[220:221], v[234:237], off
	s_mov_b32 s4, 0x44000
	v_lshl_add_u64 v[214:215], v[204:205], 0, s[4:5]
	s_waitcnt lgkmcnt(3)
	global_store_dwordx4 v[214:215], v[238:241], off
	s_mov_b32 s4, 0x55000
	v_lshl_add_u64 v[216:217], v[204:205], 0, s[4:5]
	s_waitcnt lgkmcnt(2)
	global_store_dwordx4 v[216:217], v[242:245], off
	s_mov_b32 s4, 0x66000
	v_lshl_add_u64 v[218:219], v[204:205], 0, s[4:5]
	s_waitcnt lgkmcnt(1)
	global_store_dwordx4 v[218:219], v[246:249], off
	s_mov_b32 s4, 0x77000
	v_lshl_add_u64 v[220:221], v[204:205], 0, s[4:5]
	s_waitcnt lgkmcnt(0)
	global_store_dwordx4 v[220:221], v[250:253], off
	s_waitcnt lgkmcnt(0)
	s_cmp_gt_i32 s51, 8
	v_pk_mul_f32 v[76:77], v[76:77], v[142:143] op_sel_hi:[1,0]
	v_pk_mul_f32 v[78:79], v[78:79], v[142:143] op_sel_hi:[1,0]
	v_pk_mul_f32 v[68:69], v[68:69], v[142:143] op_sel_hi:[1,0]
	v_pk_mul_f32 v[70:71], v[70:71], v[142:143] op_sel_hi:[1,0]
	s_cbranch_scc0 .Lp1e_17
	v_mul_f32_e32 v76, 0xbfb8aa3b, v76
	v_mul_f32_e32 v77, 0xbfb8aa3b, v77
	v_mul_f32_e32 v78, 0xbfb8aa3b, v78
	v_mul_f32_e32 v79, 0xbfb8aa3b, v79
	v_exp_f32_e32 v76, v76
	v_exp_f32_e32 v77, v77
	v_exp_f32_e32 v78, v78
	v_exp_f32_e32 v79, v79
	v_add_f32_e32 v76, 1.0, v76
	v_add_f32_e32 v77, 1.0, v77
	v_add_f32_e32 v78, 1.0, v78
	v_add_f32_e32 v79, 1.0, v79
	v_rcp_f32_e32 v76, v76
	v_rcp_f32_e32 v77, v77
	v_rcp_f32_e32 v78, v78
	v_rcp_f32_e32 v79, v79
.Lp1e_17:
	v_cvt_pk_bf16_f32 v206, v76, v77
	v_cvt_pk_bf16_f32 v207, v78, v79
	ds_write_b64 v196, v[206:207]
	v_pk_mul_f32 v[52:53], v[52:53], v[142:143] op_sel_hi:[1,0]
	v_pk_mul_f32 v[54:55], v[54:55], v[142:143] op_sel_hi:[1,0]
	s_cbranch_scc0 .Lp1e_18
	v_mul_f32_e32 v68, 0xbfb8aa3b, v68
	v_mul_f32_e32 v69, 0xbfb8aa3b, v69
	v_mul_f32_e32 v70, 0xbfb8aa3b, v70
	v_mul_f32_e32 v71, 0xbfb8aa3b, v71
	v_exp_f32_e32 v68, v68
	v_exp_f32_e32 v69, v69
	v_exp_f32_e32 v70, v70
	v_exp_f32_e32 v71, v71
	v_add_f32_e32 v68, 1.0, v68
	v_add_f32_e32 v69, 1.0, v69
	v_add_f32_e32 v70, 1.0, v70
	v_add_f32_e32 v71, 1.0, v71
	v_rcp_f32_e32 v68, v68
	v_rcp_f32_e32 v69, v69
	v_rcp_f32_e32 v70, v70
	v_rcp_f32_e32 v71, v71
.Lp1e_18:
	v_cvt_pk_bf16_f32 v208, v68, v69
	v_cvt_pk_bf16_f32 v209, v70, v71
	ds_write_b64 v197, v[208:209]
	v_pk_mul_f32 v[48:49], v[48:49], v[142:143] op_sel_hi:[1,0]
	v_pk_mul_f32 v[50:51], v[50:51], v[142:143] op_sel_hi:[1,0]
	s_cbranch_scc0 .Lp1e_19
	v_mul_f32_e32 v52, 0xbfb8aa3b, v52
	v_mul_f32_e32 v53, 0xbfb8aa3b, v53
	v_mul_f32_e32 v54, 0xbfb8aa3b, v54
	v_mul_f32_e32 v55, 0xbfb8aa3b, v55
	v_exp_f32_e32 v52, v52
	v_exp_f32_e32 v53, v53
	v_exp_f32_e32 v54, v54
	v_exp_f32_e32 v55, v55
	v_add_f32_e32 v52, 1.0, v52
	v_add_f32_e32 v53, 1.0, v53
	v_add_f32_e32 v54, 1.0, v54
	v_add_f32_e32 v55, 1.0, v55
	v_rcp_f32_e32 v52, v52
	v_rcp_f32_e32 v53, v53
	v_rcp_f32_e32 v54, v54
	v_rcp_f32_e32 v55, v55
.Lp1e_19:
	v_cvt_pk_bf16_f32 v210, v52, v53
	v_cvt_pk_bf16_f32 v211, v54, v55
	ds_write_b64 v198, v[210:211]
	v_pk_mul_f32 v[60:61], v[60:61], v[140:141] op_sel_hi:[1,0]
	v_pk_mul_f32 v[62:63], v[62:63], v[140:141] op_sel_hi:[1,0]
	s_cbranch_scc0 .Lp1e_20
	v_mul_f32_e32 v48, 0xbfb8aa3b, v48
	v_mul_f32_e32 v49, 0xbfb8aa3b, v49
	v_mul_f32_e32 v50, 0xbfb8aa3b, v50
	v_mul_f32_e32 v51, 0xbfb8aa3b, v51
	v_exp_f32_e32 v48, v48
	v_exp_f32_e32 v49, v49
	v_exp_f32_e32 v50, v50
	v_exp_f32_e32 v51, v51
	v_add_f32_e32 v48, 1.0, v48
	v_add_f32_e32 v49, 1.0, v49
	v_add_f32_e32 v50, 1.0, v50
	v_add_f32_e32 v51, 1.0, v51
	v_rcp_f32_e32 v48, v48
	v_rcp_f32_e32 v49, v49
	v_rcp_f32_e32 v50, v50
	v_rcp_f32_e32 v51, v51
.Lp1e_20:
	v_cvt_pk_bf16_f32 v212, v48, v49
	v_cvt_pk_bf16_f32 v213, v50, v51
	ds_write_b64 v199, v[212:213]
	v_pk_mul_f32 v[56:57], v[56:57], v[140:141] op_sel_hi:[1,0]
	v_pk_mul_f32 v[58:59], v[58:59], v[140:141] op_sel_hi:[1,0]
	s_cbranch_scc0 .Lp1e_21
	v_mul_f32_e32 v60, 0xbfb8aa3b, v60
	v_mul_f32_e32 v61, 0xbfb8aa3b, v61
	v_mul_f32_e32 v62, 0xbfb8aa3b, v62
	v_mul_f32_e32 v63, 0xbfb8aa3b, v63
	v_exp_f32_e32 v60, v60
	v_exp_f32_e32 v61, v61
	v_exp_f32_e32 v62, v62
	v_exp_f32_e32 v63, v63
	v_add_f32_e32 v60, 1.0, v60
	v_add_f32_e32 v61, 1.0, v61
	v_add_f32_e32 v62, 1.0, v62
	v_add_f32_e32 v63, 1.0, v63
	v_rcp_f32_e32 v60, v60
	v_rcp_f32_e32 v61, v61
	v_rcp_f32_e32 v62, v62
	v_rcp_f32_e32 v63, v63
.Lp1e_21:
	v_cvt_pk_bf16_f32 v206, v60, v61
	v_cvt_pk_bf16_f32 v207, v62, v63
	ds_write_b64 v196, v[206:207] offset:2048
	v_pk_mul_f32 v[36:37], v[36:37], v[140:141] op_sel_hi:[1,0]
	v_pk_mul_f32 v[38:39], v[38:39], v[140:141] op_sel_hi:[1,0]
	s_cbranch_scc0 .Lp1e_22
	v_mul_f32_e32 v56, 0xbfb8aa3b, v56
	v_mul_f32_e32 v57, 0xbfb8aa3b, v57
	v_mul_f32_e32 v58, 0xbfb8aa3b, v58
	v_mul_f32_e32 v59, 0xbfb8aa3b, v59
	v_exp_f32_e32 v56, v56
	v_exp_f32_e32 v57, v57
	v_exp_f32_e32 v58, v58
	v_exp_f32_e32 v59, v59
	v_add_f32_e32 v56, 1.0, v56
	v_add_f32_e32 v57, 1.0, v57
	v_add_f32_e32 v58, 1.0, v58
	v_add_f32_e32 v59, 1.0, v59
	v_rcp_f32_e32 v56, v56
	v_rcp_f32_e32 v57, v57
	v_rcp_f32_e32 v58, v58
	v_rcp_f32_e32 v59, v59
; template <int EPI> ...
;     ...
;         for (int h = 0; h < 2; ++h) {
; #pragma unroll
;           for (int mm = 0; mm < 4; ++mm)
; #pragma unroll
;             for (int n = 0; n < 4; ++n) {
;               f32x4 v = acc[h * 4 + mm][n] * rs[h * 4 + mm];
;               if constexpr (EPI == EPI_PROJ) {
;                 if (gate) {
; #pragma unroll
;                   for (int j = 0; j < 4; ++j) v[j] = __builtin_amdgcn_rcpf(1.0f + __expf(-v[j]));
;                 }
;               } else {
; #pragma unroll
;                 for (int j = 0; j < 4; ++j) { float r = fmaxf(v[j], 0.f); v[j] = r * r; }
;               }
;               u32x2 o = {pack2(v[0], v[1]), pack2(v[2], v[3])};
;               *(u32x2*)(wst + (mm * 16 + fr) * 128 + (((n * 2 + (fq >> 1)) ^ wswz) << 4) + (fq & 1) * 8) = o;
.Lp1e_22:
	v_cvt_pk_bf16_f32 v208, v56, v57
	v_cvt_pk_bf16_f32 v209, v58, v59
	ds_write_b64 v197, v[208:209] offset:2048
	v_pk_mul_f32 v[32:33], v[32:33], v[140:141] op_sel_hi:[1,0]
	v_pk_mul_f32 v[34:35], v[34:35], v[140:141] op_sel_hi:[1,0]
	s_cbranch_scc0 .Lp1e_23
	v_mul_f32_e32 v36, 0xbfb8aa3b, v36
	v_mul_f32_e32 v37, 0xbfb8aa3b, v37
	v_mul_f32_e32 v38, 0xbfb8aa3b, v38
	v_mul_f32_e32 v39, 0xbfb8aa3b, v39
	v_exp_f32_e32 v36, v36
	v_exp_f32_e32 v37, v37
	v_exp_f32_e32 v38, v38
	v_exp_f32_e32 v39, v39
	v_add_f32_e32 v36, 1.0, v36
	v_add_f32_e32 v37, 1.0, v37
	v_add_f32_e32 v38, 1.0, v38
	v_add_f32_e32 v39, 1.0, v39
	v_rcp_f32_e32 v36, v36
	v_rcp_f32_e32 v37, v37
	v_rcp_f32_e32 v38, v38
	v_rcp_f32_e32 v39, v39
.Lp1e_23:
	v_cvt_pk_bf16_f32 v210, v36, v37
	v_cvt_pk_bf16_f32 v211, v38, v39
	ds_write_b64 v198, v[210:211] offset:2048
	v_pk_mul_f32 v[44:45], v[44:45], v[138:139] op_sel_hi:[1,0]
	v_pk_mul_f32 v[46:47], v[46:47], v[138:139] op_sel_hi:[1,0]
	s_cbranch_scc0 .Lp1e_24
	v_mul_f32_e32 v32, 0xbfb8aa3b, v32
	v_mul_f32_e32 v33, 0xbfb8aa3b, v33
	v_mul_f32_e32 v34, 0xbfb8aa3b, v34
	v_mul_f32_e32 v35, 0xbfb8aa3b, v35
	v_exp_f32_e32 v32, v32
	v_exp_f32_e32 v33, v33
	v_exp_f32_e32 v34, v34
	v_exp_f32_e32 v35, v35
	v_add_f32_e32 v32, 1.0, v32
	v_add_f32_e32 v33, 1.0, v33
	v_add_f32_e32 v34, 1.0, v34
	v_add_f32_e32 v35, 1.0, v35
	v_rcp_f32_e32 v32, v32
	v_rcp_f32_e32 v33, v33
	v_rcp_f32_e32 v34, v34
	v_rcp_f32_e32 v35, v35
.Lp1e_24:
	v_cvt_pk_bf16_f32 v212, v32, v33
	v_cvt_pk_bf16_f32 v213, v34, v35
	ds_write_b64 v199, v[212:213] offset:2048
	v_pk_mul_f32 v[40:41], v[40:41], v[138:139] op_sel_hi:[1,0]
	v_pk_mul_f32 v[42:43], v[42:43], v[138:139] op_sel_hi:[1,0]
	s_cbranch_scc0 .Lp1e_25
	v_mul_f32_e32 v44, 0xbfb8aa3b, v44
	v_mul_f32_e32 v45, 0xbfb8aa3b, v45
	v_mul_f32_e32 v46, 0xbfb8aa3b, v46
	v_mul_f32_e32 v47, 0xbfb8aa3b, v47
	v_exp_f32_e32 v44, v44
	v_exp_f32_e32 v45, v45
	v_exp_f32_e32 v46, v46
	v_exp_f32_e32 v47, v47
	v_add_f32_e32 v44, 1.0, v44
	v_add_f32_e32 v45, 1.0, v45
	v_add_f32_e32 v46, 1.0, v46
	v_add_f32_e32 v47, 1.0, v47
	v_rcp_f32_e32 v44, v44
	v_rcp_f32_e32 v45, v45
	v_rcp_f32_e32 v46, v46
	v_rcp_f32_e32 v47, v47
.Lp1e_25:
	v_cvt_pk_bf16_f32 v206, v44, v45
	v_cvt_pk_bf16_f32 v207, v46, v47
	ds_write_b64 v196, v[206:207] offset:4096
	v_pk_mul_f32 v[20:21], v[20:21], v[138:139] op_sel_hi:[1,0]
	v_pk_mul_f32 v[22:23], v[22:23], v[138:139] op_sel_hi:[1,0]
	s_cbranch_scc0 .Lp1e_26
	v_mul_f32_e32 v40, 0xbfb8aa3b, v40
	v_mul_f32_e32 v41, 0xbfb8aa3b, v41
	v_mul_f32_e32 v42, 0xbfb8aa3b, v42
	v_mul_f32_e32 v43, 0xbfb8aa3b, v43
	v_exp_f32_e32 v40, v40
	v_exp_f32_e32 v41, v41
	v_exp_f32_e32 v42, v42
	v_exp_f32_e32 v43, v43
	v_add_f32_e32 v40, 1.0, v40
	v_add_f32_e32 v41, 1.0, v41
	v_add_f32_e32 v42, 1.0, v42
	v_add_f32_e32 v43, 1.0, v43
	v_rcp_f32_e32 v40, v40
	v_rcp_f32_e32 v41, v41
	v_rcp_f32_e32 v42, v42
	v_rcp_f32_e32 v43, v43
.Lp1e_26:
	v_cvt_pk_bf16_f32 v208, v40, v41
	v_cvt_pk_bf16_f32 v209, v42, v43
	ds_write_b64 v197, v[208:209] offset:4096
	v_pk_mul_f32 v[16:17], v[16:17], v[138:139] op_sel_hi:[1,0]
	v_pk_mul_f32 v[18:19], v[18:19], v[138:139] op_sel_hi:[1,0]
	s_cbranch_scc0 .Lp1e_27
	v_mul_f32_e32 v20, 0xbfb8aa3b, v20
	v_mul_f32_e32 v21, 0xbfb8aa3b, v21
	v_mul_f32_e32 v22, 0xbfb8aa3b, v22
	v_mul_f32_e32 v23, 0xbfb8aa3b, v23
	v_exp_f32_e32 v20, v20
	v_exp_f32_e32 v21, v21
	v_exp_f32_e32 v22, v22
	v_exp_f32_e32 v23, v23
	v_add_f32_e32 v20, 1.0, v20
	v_add_f32_e32 v21, 1.0, v21
	v_add_f32_e32 v22, 1.0, v22
	v_add_f32_e32 v23, 1.0, v23
	v_rcp_f32_e32 v20, v20
	v_rcp_f32_e32 v21, v21
	v_rcp_f32_e32 v22, v22
	v_rcp_f32_e32 v23, v23
.Lp1e_27:
	v_cvt_pk_bf16_f32 v210, v20, v21
	v_cvt_pk_bf16_f32 v211, v22, v23
	ds_write_b64 v198, v[210:211] offset:4096
	v_pk_mul_f32 v[28:29], v[28:29], v[136:137] op_sel_hi:[1,0]
	v_pk_mul_f32 v[30:31], v[30:31], v[136:137] op_sel_hi:[1,0]
	s_cbranch_scc0 .Lp1e_28
	v_mul_f32_e32 v16, 0xbfb8aa3b, v16
	v_mul_f32_e32 v17, 0xbfb8aa3b, v17
	v_mul_f32_e32 v18, 0xbfb8aa3b, v18
	v_mul_f32_e32 v19, 0xbfb8aa3b, v19
	v_exp_f32_e32 v16, v16
	v_exp_f32_e32 v17, v17
	v_exp_f32_e32 v18, v18
	v_exp_f32_e32 v19, v19
	v_add_f32_e32 v16, 1.0, v16
	v_add_f32_e32 v17, 1.0, v17
	v_add_f32_e32 v18, 1.0, v18
	v_add_f32_e32 v19, 1.0, v19
	v_rcp_f32_e32 v16, v16
	v_rcp_f32_e32 v17, v17
	v_rcp_f32_e32 v18, v18
	v_rcp_f32_e32 v19, v19
; #define WAIT_V(n) asm volatile("s_waitcnt vmcnt(%0)" ::"n"(n) : "memory")
; #define LDS_FENCE() asm volatile("s_waitcnt lgkmcnt(0)" ::: "memory")
; template <int EPI> ...
;     ...
;         for (int h = 0; h < 2; ++h) {
; #pragma unroll
;           for (int mm = 0; mm < 4; ++mm)
; #pragma unroll
;             for (int n = 0; n < 4; ++n) {
;               f32x4 v = acc[h * 4 + mm][n] * rs[h * 4 + mm];
;               if constexpr (EPI == EPI_PROJ) {
;                 if (gate) {
; #pragma unroll
;                   for (int j = 0; j < 4; ++j) v[j] = __builtin_amdgcn_rcpf(1.0f + __expf(-v[j]));
;                 }
;               } else {
; #pragma unroll
;                 for (int j = 0; j < 4; ++j) { float r = fmaxf(v[j], 0.f); v[j] = r * r; }
;               }
;               u32x2 o = {pack2(v[0], v[1]), pack2(v[2], v[3])};
;               *(u32x2*)(wst + (mm * 16 + fr) * 128 + (((n * 2 + (fq >> 1)) ^ wswz) << 4) + (fq & 1) * 8) = o;
;             }
;           LDS_FENCE();
;           if (h == 0) WAIT_V(0);
; #pragma unroll
;           for (int i = 0; i < 8; ++i) {
;             const u32x4 d = *(const u32x4*)(wst + (i * 8 + (lane >> 3)) * 128 + (((lane & 7) ^ rswz) << 4));
;             *(u32x4*)(gout + (long)(h * 64 + i * 8) * ld) = d;
;           }
;           LDS_FENCE();
.Lp1e_28:
	v_cvt_pk_bf16_f32 v212, v16, v17
	v_cvt_pk_bf16_f32 v213, v18, v19
	ds_write_b64 v199, v[212:213] offset:4096
	v_pk_mul_f32 v[24:25], v[24:25], v[136:137] op_sel_hi:[1,0]
	v_pk_mul_f32 v[26:27], v[26:27], v[136:137] op_sel_hi:[1,0]
	s_cbranch_scc0 .Lp1e_29
	v_mul_f32_e32 v28, 0xbfb8aa3b, v28
	v_mul_f32_e32 v29, 0xbfb8aa3b, v29
	v_mul_f32_e32 v30, 0xbfb8aa3b, v30
	v_mul_f32_e32 v31, 0xbfb8aa3b, v31
	v_exp_f32_e32 v28, v28
	v_exp_f32_e32 v29, v29
	v_exp_f32_e32 v30, v30
	v_exp_f32_e32 v31, v31
	v_add_f32_e32 v28, 1.0, v28
	v_add_f32_e32 v29, 1.0, v29
	v_add_f32_e32 v30, 1.0, v30
	v_add_f32_e32 v31, 1.0, v31
	v_rcp_f32_e32 v28, v28
	v_rcp_f32_e32 v29, v29
	v_rcp_f32_e32 v30, v30
	v_rcp_f32_e32 v31, v31
.Lp1e_29:
	v_cvt_pk_bf16_f32 v206, v28, v29
	v_cvt_pk_bf16_f32 v207, v30, v31
	ds_write_b64 v196, v[206:207] offset:6144
	v_pk_mul_f32 v[12:13], v[12:13], v[136:137] op_sel_hi:[1,0]
	v_pk_mul_f32 v[14:15], v[14:15], v[136:137] op_sel_hi:[1,0]
	s_cbranch_scc0 .Lp1e_30
	v_mul_f32_e32 v24, 0xbfb8aa3b, v24
	v_mul_f32_e32 v25, 0xbfb8aa3b, v25
	v_mul_f32_e32 v26, 0xbfb8aa3b, v26
	v_mul_f32_e32 v27, 0xbfb8aa3b, v27
	v_exp_f32_e32 v24, v24
	v_exp_f32_e32 v25, v25
	v_exp_f32_e32 v26, v26
	v_exp_f32_e32 v27, v27
	v_add_f32_e32 v24, 1.0, v24
	v_add_f32_e32 v25, 1.0, v25
	v_add_f32_e32 v26, 1.0, v26
	v_add_f32_e32 v27, 1.0, v27
	v_rcp_f32_e32 v24, v24
	v_rcp_f32_e32 v25, v25
	v_rcp_f32_e32 v26, v26
	v_rcp_f32_e32 v27, v27
.Lp1e_30:
	v_cvt_pk_bf16_f32 v208, v24, v25
	v_cvt_pk_bf16_f32 v209, v26, v27
	ds_write_b64 v197, v[208:209] offset:6144
	v_pk_mul_f32 v[8:9], v[8:9], v[136:137] op_sel_hi:[1,0]
	v_pk_mul_f32 v[10:11], v[10:11], v[136:137] op_sel_hi:[1,0]
	s_cbranch_scc0 .Lp1e_31
	v_mul_f32_e32 v12, 0xbfb8aa3b, v12
	v_mul_f32_e32 v13, 0xbfb8aa3b, v13
	v_mul_f32_e32 v14, 0xbfb8aa3b, v14
	v_mul_f32_e32 v15, 0xbfb8aa3b, v15
	v_exp_f32_e32 v12, v12
	v_exp_f32_e32 v13, v13
	v_exp_f32_e32 v14, v14
	v_exp_f32_e32 v15, v15
	v_add_f32_e32 v12, 1.0, v12
	v_add_f32_e32 v13, 1.0, v13
	v_add_f32_e32 v14, 1.0, v14
	v_add_f32_e32 v15, 1.0, v15
	v_rcp_f32_e32 v12, v12
	v_rcp_f32_e32 v13, v13
	v_rcp_f32_e32 v14, v14
	v_rcp_f32_e32 v15, v15
.Lp1e_31:
	v_cvt_pk_bf16_f32 v210, v12, v13
	v_cvt_pk_bf16_f32 v211, v14, v15
	ds_write_b64 v198, v[210:211] offset:6144
	s_cbranch_scc0 .Lp1e_32
	v_mul_f32_e32 v8, 0xbfb8aa3b, v8
	v_mul_f32_e32 v9, 0xbfb8aa3b, v9
	v_mul_f32_e32 v10, 0xbfb8aa3b, v10
	v_mul_f32_e32 v11, 0xbfb8aa3b, v11
	v_exp_f32_e32 v8, v8
	v_exp_f32_e32 v9, v9
	v_exp_f32_e32 v10, v10
	v_exp_f32_e32 v11, v11
	v_add_f32_e32 v8, 1.0, v8
	v_add_f32_e32 v9, 1.0, v9
	v_add_f32_e32 v10, 1.0, v10
	v_add_f32_e32 v11, 1.0, v11
	v_rcp_f32_e32 v8, v8
	v_rcp_f32_e32 v9, v9
	v_rcp_f32_e32 v10, v10
	v_rcp_f32_e32 v11, v11
.Lp1e_32:
	v_cvt_pk_bf16_f32 v212, v8, v9
	v_cvt_pk_bf16_f32 v213, v10, v11
	ds_write_b64 v199, v[212:213] offset:6144
	s_waitcnt lgkmcnt(0)
	ds_read_b128 v[222:225], v202
	ds_read_b128 v[226:229], v202 offset:1024
	ds_read_b128 v[230:233], v202 offset:2048
	ds_read_b128 v[234:237], v202 offset:3072
	ds_read_b128 v[238:241], v202 offset:4096
	ds_read_b128 v[242:245], v202 offset:5120
	ds_read_b128 v[246:249], v202 offset:6144
	ds_read_b128 v[250:253], v202 offset:7168
	s_mov_b32 s4, 0x88000
	v_lshl_add_u64 v[214:215], v[204:205], 0, s[4:5]
	s_waitcnt lgkmcnt(7)
	global_store_dwordx4 v[214:215], v[222:225], off
	s_mov_b32 s4, 0x99000
	v_lshl_add_u64 v[216:217], v[204:205], 0, s[4:5]
	s_waitcnt lgkmcnt(6)
	global_store_dwordx4 v[216:217], v[226:229], off
	s_mov_b32 s4, 0xaa000
	v_lshl_add_u64 v[218:219], v[204:205], 0, s[4:5]
	s_waitcnt lgkmcnt(5)
	global_store_dwordx4 v[218:219], v[230:233], off
	s_mov_b32 s4, 0xbb000
	v_lshl_add_u64 v[220:221], v[204:205], 0, s[4:5]
	s_waitcnt lgkmcnt(4)
	global_store_dwordx4 v[220:221], v[234:237], off
	s_mov_b32 s4, 0xcc000
	v_lshl_add_u64 v[214:215], v[204:205], 0, s[4:5]
	s_waitcnt lgkmcnt(3)
	global_store_dwordx4 v[214:215], v[238:241], off
	s_mov_b32 s4, 0xdd000
	v_lshl_add_u64 v[216:217], v[204:205], 0, s[4:5]
	s_waitcnt lgkmcnt(2)
	global_store_dwordx4 v[216:217], v[242:245], off
	s_mov_b32 s4, 0xee000
	v_lshl_add_u64 v[218:219], v[204:205], 0, s[4:5]
	s_waitcnt lgkmcnt(1)
	global_store_dwordx4 v[218:219], v[246:249], off
	s_mov_b32 s4, 0xff000
	v_lshl_add_u64 v[220:221], v[204:205], 0, s[4:5]
	s_waitcnt lgkmcnt(0)
	global_store_dwordx4 v[220:221], v[250:253], off
	s_waitcnt lgkmcnt(0)
